# K-loop 6-DMA load segments: LDS-DMA issue before the 8 ds_reads
# speedup vs baseline: 1.0113x; 1.0113x over previous
.LBB0_169:
	s_add_i32 s0, s34, 2
	s_add_u32 s1, s80, 0x80
	s_addc_u32 s35, s81, 0
	s_add_i32 s47, 0, 0x10000
	s_cmp_eq_u32 s68, s34
	s_cselect_b32 s35, s43, s35
	s_cselect_b32 s34, s42, s1
	s_cselect_b32 s67, s87, vcc_hi
	s_cselect_b32 s66, s86, vcc_lo
	s_add_i32 s1, 0, 0x14000
	s_waitcnt lgkmcnt(0)
	ds_read_b128 v[130:133], v206
	ds_read_b128 v[134:137], v206 offset:1024
	ds_read_b128 v[138:141], v206 offset:2048
	ds_read_b128 v[142:145], v206 offset:3072
	ds_read_b128 v[146:149], v207
	ds_read_b128 v[150:153], v207 offset:1024
	ds_read_b128 v[154:157], v207 offset:2048
	ds_read_b128 v[158:161], v207 offset:3072
	s_add_i32 m0, s90, 0xc000
	ds_read_b128 v[162:165], v238
	ds_read_b128 v[166:169], v238 offset:1024
	ds_read_b128 v[170:173], v238 offset:2048
	ds_read_b128 v[174:177], v238 offset:3072
	ds_read_b128 v[178:181], v238 offset:4096
	ds_read_b128 v[182:185], v238 offset:5120
	ds_read_b128 v[198:201], v238 offset:6144
	ds_read_b128 v[202:205], v238 offset:7168
	global_load_lds_dwordx4 v194, s[80:81]
	s_add_i32 m0, s90, 0xe000
	s_nop 0
	global_load_lds_dwordx4 v196, s[80:81]
	s_waitcnt vmcnt(8)
	s_waitcnt lgkmcnt(0)
	s_barrier
	s_setprio 1
	v_mfma_f32_16x16x32_bf16 v[126:129], v[130:133], v[162:165], v[126:129]
	v_mfma_f32_16x16x32_bf16 v[122:125], v[138:141], v[162:165], v[122:125]
	v_mfma_f32_16x16x32_bf16 v[118:121], v[130:133], v[170:173], v[118:121]
	v_mfma_f32_16x16x32_bf16 v[102:105], v[138:141], v[170:173], v[102:105]
	v_mfma_f32_16x16x32_bf16 v[94:97], v[130:133], v[178:181], v[94:97]
	v_mfma_f32_16x16x32_bf16 v[90:93], v[138:141], v[178:181], v[90:93]
	v_mfma_f32_16x16x32_bf16 v[78:81], v[130:133], v[198:201], v[78:81]
	v_mfma_f32_16x16x32_bf16 v[74:77], v[138:141], v[198:201], v[74:77]
	v_mfma_f32_16x16x32_bf16 v[126:129], v[134:137], v[166:169], v[126:129]
	v_mfma_f32_16x16x32_bf16 v[122:125], v[142:145], v[166:169], v[122:125]
	v_mfma_f32_16x16x32_bf16 v[118:121], v[134:137], v[174:177], v[118:121]
	v_mfma_f32_16x16x32_bf16 v[102:105], v[142:145], v[174:177], v[102:105]
	v_mfma_f32_16x16x32_bf16 v[94:97], v[134:137], v[182:185], v[94:97]
	v_mfma_f32_16x16x32_bf16 v[90:93], v[142:145], v[182:185], v[90:93]
	v_mfma_f32_16x16x32_bf16 v[78:81], v[134:137], v[202:205], v[78:81]
	v_mfma_f32_16x16x32_bf16 v[74:77], v[142:145], v[202:205], v[74:77]
	v_mfma_f32_16x16x32_bf16 v[114:117], v[146:149], v[162:165], v[114:117]
	v_mfma_f32_16x16x32_bf16 v[110:113], v[154:157], v[162:165], v[110:113]
	v_mfma_f32_16x16x32_bf16 v[106:109], v[146:149], v[170:173], v[106:109]
	v_mfma_f32_16x16x32_bf16 v[98:101], v[154:157], v[170:173], v[98:101]
	v_mfma_f32_16x16x32_bf16 v[86:89], v[146:149], v[178:181], v[86:89]
	v_mfma_f32_16x16x32_bf16 v[82:85], v[154:157], v[178:181], v[82:85]
	v_mfma_f32_16x16x32_bf16 v[70:73], v[146:149], v[198:201], v[70:73]
	v_mfma_f32_16x16x32_bf16 v[66:69], v[154:157], v[198:201], v[66:69]
	v_mfma_f32_16x16x32_bf16 v[114:117], v[150:153], v[166:169], v[114:117]
	v_mfma_f32_16x16x32_bf16 v[110:113], v[158:161], v[166:169], v[110:113]
	v_mfma_f32_16x16x32_bf16 v[106:109], v[150:153], v[174:177], v[106:109]
	v_mfma_f32_16x16x32_bf16 v[98:101], v[158:161], v[174:177], v[98:101]
	v_mfma_f32_16x16x32_bf16 v[86:89], v[150:153], v[182:185], v[86:89]
	v_mfma_f32_16x16x32_bf16 v[82:85], v[158:161], v[182:185], v[82:85]
	v_mfma_f32_16x16x32_bf16 v[70:73], v[150:153], v[202:205], v[70:73]
	v_mfma_f32_16x16x32_bf16 v[66:69], v[158:161], v[202:205], v[66:69]
	s_setprio 0
	s_barrier
	s_add_i32 s47, s47, s57
	s_mov_b32 m0, s47
	s_nop 0
	global_load_lds_dwordx4 v188, s[66:67]
	s_add_i32 m0, s47, 0x2000
	s_add_u32 s100, s66, s69
	s_addc_u32 s101, s67, 0
	s_add_i32 s1, s1, s57
	global_load_lds_dwordx4 v192, s[66:67]
	s_mov_b32 m0, s1
	s_nop 0
	global_load_lds_dwordx4 v188, s[100:101]
	s_add_i32 m0, s1, 0x2000
	s_nop 0
	global_load_lds_dwordx4 v192, s[100:101]
	s_mov_b32 m0, s90
	s_nop 0
	global_load_lds_dwordx4 v186, s[34:35]
	s_mov_b32 m0, s60
	s_nop 0
	global_load_lds_dwordx4 v190, s[34:35]
	ds_read_b128 v[162:165], v238 offset:16384
	ds_read_b128 v[166:169], v238 offset:17408
	ds_read_b128 v[170:173], v238 offset:18432
	ds_read_b128 v[174:177], v238 offset:19456
	ds_read_b128 v[178:181], v238 offset:20480
	ds_read_b128 v[182:185], v238 offset:21504
	ds_read_b128 v[198:201], v238 offset:22528
	ds_read_b128 v[202:205], v238 offset:23552
	s_waitcnt vmcnt(8)
	s_waitcnt lgkmcnt(0)
	s_barrier
	s_setprio 1
	v_mfma_f32_16x16x32_bf16 v[62:65], v[130:133], v[162:165], v[62:65]
	v_mfma_f32_16x16x32_bf16 v[58:61], v[138:141], v[162:165], v[58:61]
	v_mfma_f32_16x16x32_bf16 v[46:49], v[130:133], v[170:173], v[46:49]
	v_mfma_f32_16x16x32_bf16 v[42:45], v[138:141], v[170:173], v[42:45]
	v_mfma_f32_16x16x32_bf16 v[30:33], v[130:133], v[178:181], v[30:33]
	v_mfma_f32_16x16x32_bf16 v[26:29], v[138:141], v[178:181], v[26:29]
	v_mfma_f32_16x16x32_bf16 v[14:17], v[130:133], v[198:201], v[14:17]
	v_mfma_f32_16x16x32_bf16 v[10:13], v[138:141], v[198:201], v[10:13]
	v_mfma_f32_16x16x32_bf16 v[62:65], v[134:137], v[166:169], v[62:65]
	v_mfma_f32_16x16x32_bf16 v[58:61], v[142:145], v[166:169], v[58:61]
	v_mfma_f32_16x16x32_bf16 v[46:49], v[134:137], v[174:177], v[46:49]
	v_mfma_f32_16x16x32_bf16 v[42:45], v[142:145], v[174:177], v[42:45]
	v_mfma_f32_16x16x32_bf16 v[30:33], v[134:137], v[182:185], v[30:33]
	v_mfma_f32_16x16x32_bf16 v[26:29], v[142:145], v[182:185], v[26:29]
	v_mfma_f32_16x16x32_bf16 v[14:17], v[134:137], v[202:205], v[14:17]
	v_mfma_f32_16x16x32_bf16 v[10:13], v[142:145], v[202:205], v[10:13]
	v_mfma_f32_16x16x32_bf16 v[54:57], v[146:149], v[162:165], v[54:57]
	v_mfma_f32_16x16x32_bf16 v[50:53], v[154:157], v[162:165], v[50:53]
	v_mfma_f32_16x16x32_bf16 v[38:41], v[146:149], v[170:173], v[38:41]
	v_mfma_f32_16x16x32_bf16 v[34:37], v[154:157], v[170:173], v[34:37]
	v_mfma_f32_16x16x32_bf16 v[22:25], v[146:149], v[178:181], v[22:25]
	v_mfma_f32_16x16x32_bf16 v[18:21], v[154:157], v[178:181], v[18:21]
	v_mfma_f32_16x16x32_bf16 v[6:9], v[146:149], v[198:201], v[6:9]
	v_mfma_f32_16x16x32_bf16 v[2:5], v[154:157], v[198:201], v[2:5]
	v_mfma_f32_16x16x32_bf16 v[54:57], v[150:153], v[166:169], v[54:57]
	v_mfma_f32_16x16x32_bf16 v[50:53], v[158:161], v[166:169], v[50:53]
	v_mfma_f32_16x16x32_bf16 v[38:41], v[150:153], v[174:177], v[38:41]
	v_mfma_f32_16x16x32_bf16 v[34:37], v[158:161], v[174:177], v[34:37]
	v_mfma_f32_16x16x32_bf16 v[22:25], v[150:153], v[182:185], v[22:25]
	v_mfma_f32_16x16x32_bf16 v[18:21], v[158:161], v[182:185], v[18:21]
	v_mfma_f32_16x16x32_bf16 v[6:9], v[150:153], v[202:205], v[6:9]
	v_mfma_f32_16x16x32_bf16 v[2:5], v[158:161], v[202:205], v[2:5]
	s_setprio 0
	s_barrier
	s_add_i32 s1, 0, 0x18000
	s_add_i32 s47, 0, 0x1c000
	ds_read_b128 v[130:133], v208
	ds_read_b128 v[134:137], v208 offset:1024
	ds_read_b128 v[138:141], v208 offset:2048
	ds_read_b128 v[142:145], v208 offset:3072
	ds_read_b128 v[146:149], v209
	ds_read_b128 v[150:153], v209 offset:1024
	ds_read_b128 v[154:157], v209 offset:2048
	ds_read_b128 v[158:161], v209 offset:3072
	s_mov_b32 m0, s61
	ds_read_b128 v[162:165], v238 offset:32768
	ds_read_b128 v[166:169], v238 offset:33792
	ds_read_b128 v[170:173], v238 offset:34816
	ds_read_b128 v[174:177], v238 offset:35840
	ds_read_b128 v[178:181], v238 offset:36864
	ds_read_b128 v[182:185], v238 offset:37888
	ds_read_b128 v[198:201], v238 offset:38912
	ds_read_b128 v[202:205], v238 offset:39936
	global_load_lds_dwordx4 v194, s[34:35]
	s_mov_b32 m0, s71
	s_nop 0
	global_load_lds_dwordx4 v196, s[34:35]
	s_waitcnt vmcnt(8)
	s_waitcnt lgkmcnt(0)
	s_barrier
	s_setprio 1
	v_mfma_f32_16x16x32_bf16 v[126:129], v[130:133], v[162:165], v[126:129]
	v_mfma_f32_16x16x32_bf16 v[122:125], v[138:141], v[162:165], v[122:125]
	v_mfma_f32_16x16x32_bf16 v[118:121], v[130:133], v[170:173], v[118:121]
	v_mfma_f32_16x16x32_bf16 v[102:105], v[138:141], v[170:173], v[102:105]
	v_mfma_f32_16x16x32_bf16 v[94:97], v[130:133], v[178:181], v[94:97]
	v_mfma_f32_16x16x32_bf16 v[90:93], v[138:141], v[178:181], v[90:93]
	v_mfma_f32_16x16x32_bf16 v[78:81], v[130:133], v[198:201], v[78:81]
	v_mfma_f32_16x16x32_bf16 v[74:77], v[138:141], v[198:201], v[74:77]
	v_mfma_f32_16x16x32_bf16 v[126:129], v[134:137], v[166:169], v[126:129]
	v_mfma_f32_16x16x32_bf16 v[122:125], v[142:145], v[166:169], v[122:125]
	v_mfma_f32_16x16x32_bf16 v[118:121], v[134:137], v[174:177], v[118:121]
	v_mfma_f32_16x16x32_bf16 v[102:105], v[142:145], v[174:177], v[102:105]
	v_mfma_f32_16x16x32_bf16 v[94:97], v[134:137], v[182:185], v[94:97]
	v_mfma_f32_16x16x32_bf16 v[90:93], v[142:145], v[182:185], v[90:93]
	v_mfma_f32_16x16x32_bf16 v[78:81], v[134:137], v[202:205], v[78:81]
	v_mfma_f32_16x16x32_bf16 v[74:77], v[142:145], v[202:205], v[74:77]
	v_mfma_f32_16x16x32_bf16 v[114:117], v[146:149], v[162:165], v[114:117]
	v_mfma_f32_16x16x32_bf16 v[110:113], v[154:157], v[162:165], v[110:113]
	v_mfma_f32_16x16x32_bf16 v[106:109], v[146:149], v[170:173], v[106:109]
	v_mfma_f32_16x16x32_bf16 v[98:101], v[154:157], v[170:173], v[98:101]
	v_mfma_f32_16x16x32_bf16 v[86:89], v[146:149], v[178:181], v[86:89]
	v_mfma_f32_16x16x32_bf16 v[82:85], v[154:157], v[178:181], v[82:85]
	v_mfma_f32_16x16x32_bf16 v[70:73], v[146:149], v[198:201], v[70:73]
	v_mfma_f32_16x16x32_bf16 v[66:69], v[154:157], v[198:201], v[66:69]
	v_mfma_f32_16x16x32_bf16 v[114:117], v[150:153], v[166:169], v[114:117]
	v_mfma_f32_16x16x32_bf16 v[110:113], v[158:161], v[166:169], v[110:113]
	v_mfma_f32_16x16x32_bf16 v[106:109], v[150:153], v[174:177], v[106:109]
	v_mfma_f32_16x16x32_bf16 v[98:101], v[158:161], v[174:177], v[98:101]
	v_mfma_f32_16x16x32_bf16 v[86:89], v[150:153], v[182:185], v[86:89]
	v_mfma_f32_16x16x32_bf16 v[82:85], v[158:161], v[182:185], v[82:85]
	v_mfma_f32_16x16x32_bf16 v[70:73], v[150:153], v[202:205], v[70:73]
	v_mfma_f32_16x16x32_bf16 v[66:69], v[158:161], v[202:205], v[66:69]
	s_setprio 0
	s_barrier
	s_add_i32 s1, s1, s57
	s_add_u32 s66, s66, 0x80
	s_addc_u32 s67, s67, 0
	s_add_u32 s100, s100, 0x80
	s_addc_u32 s101, s101, 0
	s_add_u32 s34, s34, 0x80
	s_addc_u32 s35, s35, 0
	s_mov_b32 m0, s1
	s_nop 0
	global_load_lds_dwordx4 v188, s[66:67]
	s_add_i32 m0, s1, 0x2000
	s_add_i32 s1, s47, s57
	global_load_lds_dwordx4 v192, s[66:67]
	s_mov_b32 m0, s1
	s_nop 0
	global_load_lds_dwordx4 v188, s[100:101]
	s_add_i32 m0, s1, 0x2000
	s_nop 0
	global_load_lds_dwordx4 v192, s[100:101]
	s_mov_b32 m0, s64
	s_nop 0
	global_load_lds_dwordx4 v186, s[34:35]
	s_mov_b32 m0, s65
	s_nop 0
	global_load_lds_dwordx4 v190, s[34:35]
	ds_read_b128 v[162:165], v238 offset:49152
	ds_read_b128 v[166:169], v238 offset:50176
	ds_read_b128 v[170:173], v238 offset:51200
	ds_read_b128 v[174:177], v238 offset:52224
	ds_read_b128 v[178:181], v238 offset:53248
	ds_read_b128 v[182:185], v238 offset:54272
	ds_read_b128 v[198:201], v238 offset:55296
	ds_read_b128 v[202:205], v238 offset:56320
	s_waitcnt vmcnt(8)
	s_waitcnt lgkmcnt(0)
	s_barrier
	s_setprio 1
	v_mfma_f32_16x16x32_bf16 v[62:65], v[130:133], v[162:165], v[62:65]
	v_mfma_f32_16x16x32_bf16 v[58:61], v[138:141], v[162:165], v[58:61]
	v_mfma_f32_16x16x32_bf16 v[46:49], v[130:133], v[170:173], v[46:49]
	v_mfma_f32_16x16x32_bf16 v[42:45], v[138:141], v[170:173], v[42:45]
	v_mfma_f32_16x16x32_bf16 v[30:33], v[130:133], v[178:181], v[30:33]
	v_mfma_f32_16x16x32_bf16 v[26:29], v[138:141], v[178:181], v[26:29]
	v_mfma_f32_16x16x32_bf16 v[14:17], v[130:133], v[198:201], v[14:17]
	v_mfma_f32_16x16x32_bf16 v[10:13], v[138:141], v[198:201], v[10:13]
	v_mfma_f32_16x16x32_bf16 v[62:65], v[134:137], v[166:169], v[62:65]
	v_mfma_f32_16x16x32_bf16 v[58:61], v[142:145], v[166:169], v[58:61]
	v_mfma_f32_16x16x32_bf16 v[46:49], v[134:137], v[174:177], v[46:49]
	v_mfma_f32_16x16x32_bf16 v[42:45], v[142:145], v[174:177], v[42:45]
	v_mfma_f32_16x16x32_bf16 v[30:33], v[134:137], v[182:185], v[30:33]
	v_mfma_f32_16x16x32_bf16 v[26:29], v[142:145], v[182:185], v[26:29]
	v_mfma_f32_16x16x32_bf16 v[14:17], v[134:137], v[202:205], v[14:17]
	v_mfma_f32_16x16x32_bf16 v[10:13], v[142:145], v[202:205], v[10:13]
	v_mfma_f32_16x16x32_bf16 v[54:57], v[146:149], v[162:165], v[54:57]
	v_mfma_f32_16x16x32_bf16 v[50:53], v[154:157], v[162:165], v[50:53]
	v_mfma_f32_16x16x32_bf16 v[38:41], v[146:149], v[170:173], v[38:41]
	v_mfma_f32_16x16x32_bf16 v[34:37], v[154:157], v[170:173], v[34:37]
	v_mfma_f32_16x16x32_bf16 v[22:25], v[146:149], v[178:181], v[22:25]
	v_mfma_f32_16x16x32_bf16 v[18:21], v[154:157], v[178:181], v[18:21]
	v_mfma_f32_16x16x32_bf16 v[6:9], v[146:149], v[198:201], v[6:9]
	v_mfma_f32_16x16x32_bf16 v[2:5], v[154:157], v[198:201], v[2:5]
	v_mfma_f32_16x16x32_bf16 v[54:57], v[150:153], v[166:169], v[54:57]
	v_mfma_f32_16x16x32_bf16 v[50:53], v[158:161], v[166:169], v[50:53]
	v_mfma_f32_16x16x32_bf16 v[38:41], v[150:153], v[174:177], v[38:41]
	v_mfma_f32_16x16x32_bf16 v[34:37], v[158:161], v[174:177], v[34:37]
	v_mfma_f32_16x16x32_bf16 v[22:25], v[150:153], v[182:185], v[22:25]
	v_mfma_f32_16x16x32_bf16 v[18:21], v[158:161], v[182:185], v[18:21]
	v_mfma_f32_16x16x32_bf16 v[6:9], v[150:153], v[202:205], v[6:9]
	v_mfma_f32_16x16x32_bf16 v[2:5], v[158:161], v[202:205], v[2:5]
	s_setprio 0
	s_barrier
	s_add_u32 s80, s80, 0x100
	s_addc_u32 s81, s81, 0
	s_add_u32 vcc_lo, vcc_lo, 0x100
	s_addc_u32 vcc_hi, vcc_hi, 0
	s_cmp_ge_u32 s0, s91
	s_mov_b32 s34, s0
	s_cbranch_scc0 .LBB0_169
	v_readlane_b32 s0, v243, 28
	v_readlane_b32 s1, v243, 29
	s_and_b64 vcc, exec, s[0:1]
	s_cbranch_vccz .LBB0_174
	s_barrier
	v_lshl_add_u32 v198, s99, 8, v1
	s_cmp_lt_i32 s70, 1
	s_mov_b64 s[34:35], -1
	s_cbranch_scc0 .LBB0_175
